# attention S^T k-steps 1-3: LDS reads pipelined 3-7 deep with renamed temps (bit-identical math)
# baseline (speedup 1.0000x reference)
; #define LAS __attribute__((address_space(3)))
; #define WG_BARRIER() do { asm volatile("s_waitcnt lgkmcnt(0)" ::: "memory"); __builtin_amdgcn_s_barrier(); asm volatile("" ::: "memory"); } while (0)
; #define MFMA16(a, b, c) __builtin_amdgcn_mfma_f32_16x16x32_bf16((a), (b), (c), 0, 0, 0)
; __device__ __forceinline__ void attention_item(LAS unsigned char* lds, const bf16* ZH, bf16* OP, float* LP, bf16* MIX, const float* qg, const float* kg, int item, int tid0) {
;     ...
;         WG_BARRIER();
; #pragma unroll
;         for (int p = 0; p < 8; ++p) if (p >= 4 || B.b == 0) { const int slot = (32 * p + krow + off) & 255;
;             *(LAS v4u*)(lds + A_K + slot * RS + 16 * kc) = kq[p];
;             *(LAS v4u*)(lds + A_V + slot * RSB + 16 * kc) = vq[p]; }
;         WG_BARRIER();
;         f32x4 sT[10];
; #pragma unroll
;         for (int t = 0; t < 10; ++t) sT[t] = (f32x4){0.f, 0.f, 0.f, 0.f};
; #pragma unroll
;         for (int ks = 0; ks < 4; ++ks) {
; #pragma unroll
;             for (int t = 0; t < 10; ++t) { const int rowb = (16 * (jt0 + t) + off) & 255;
;                 const bf16x8 a = *(const LAS bf16x8*)(lds + A_K + (rowb + lr) * RS + (8 * lg + 32 * ks) * 2); sT[t] = MFMA16(a, qf[ks], sT[t]);
.LBB0_381:
	s_lshl_b32 s56, s56, 7
	v_and_b32_e32 v4, 3, v5
	v_add_u32_e32 v5, s56, v5
	v_bitop3_b32 v150, v5, s91, v238 bitop3:0x6c
	v_mul_u32_u24_e32 v151, 0x110, v150
	v_mul_u32_u24_e32 v150, 0x120, v150
	v_add3_u32 v151, 0, v151, v2
	v_add3_u32 v150, s92, v150, v2
	s_waitcnt vmcnt(5)
	ds_write_b128 v151, v[58:61]
	s_waitcnt vmcnt(4)
	ds_write_b128 v150, v[54:57]
	v_add_u32_e32 v150, 0xa0, v5
	v_mul_u32_u24_sdwa v151, v150, s33 dst_sel:DWORD dst_unused:UNUSED_PAD src0_sel:BYTE_0 src1_sel:DWORD
	v_mul_u32_u24_sdwa v150, v150, s74 dst_sel:DWORD dst_unused:UNUSED_PAD src0_sel:BYTE_0 src1_sel:DWORD
	v_add3_u32 v151, 0, v151, v2
	v_add3_u32 v150, s92, v150, v2
	ds_write_b128 v151, v[42:45]
	ds_write_b128 v150, v[62:65]
	v_add_u32_e32 v150, 0xc0, v5
	v_mul_u32_u24_sdwa v151, v150, s33 dst_sel:DWORD dst_unused:UNUSED_PAD src0_sel:BYTE_0 src1_sel:DWORD
	v_mul_u32_u24_sdwa v150, v150, s74 dst_sel:DWORD dst_unused:UNUSED_PAD src0_sel:BYTE_0 src1_sel:DWORD
	v_add3_u32 v151, 0, v151, v2
	v_add3_u32 v150, s92, v150, v2
	v_add_u32_e32 v5, 0xe0, v5
	v_ashrrev_i32_e32 v182, 2, v209
	ds_write_b128 v151, v[94:97]
	ds_write_b128 v150, v[90:93]
	v_mul_u32_u24_sdwa v150, v5, s33 dst_sel:DWORD dst_unused:UNUSED_PAD src0_sel:BYTE_0 src1_sel:DWORD
	v_mul_u32_u24_sdwa v5, v5, s74 dst_sel:DWORD dst_unused:UNUSED_PAD src0_sel:BYTE_0 src1_sel:DWORD
	v_and_b32_e32 v210, 0xffffffe0, v182
	v_add3_u32 v150, 0, v150, v2
	v_add3_u32 v2, s92, v5, v2
	v_add_u32_e32 v207, s56, v210
	ds_write_b128 v150, v[106:109]
	ds_write_b128 v2, v[110:113]
	v_and_b32_e32 v2, 15, v209
	v_and_b32_e32 v206, 0xe0, v207
	v_or_b32_e32 v5, v206, v2
	v_lshlrev_b32_e32 v186, 4, v4
	v_mul_u32_u24_e32 v5, 0x110, v5
	v_add3_u32 v208, 0, v5, v186
	v_or_b32_e32 v5, 16, v182
	v_add_u32_e32 v5, s56, v5
	v_and_or_b32 v5, v5, s30, v2
	v_mul_u32_u24_e32 v5, 0x110, v5
	v_add3_u32 v211, 0, v5, v186
	v_and_b32_e32 v5, -16, v182
	v_add_u32_e32 v174, s56, v5
	v_add_u32_e32 v158, 32, v174
	v_add_u32_e32 v162, 48, v207
	v_add_u32_e32 v166, 64, v174
	v_and_or_b32 v158, v158, s90, v2
	v_and_or_b32 v162, v162, s30, v2
	v_and_or_b32 v166, v166, s90, v2
	v_mul_u32_u24_e32 v158, 0x110, v158
	v_mul_u32_u24_e32 v162, 0x110, v162
	v_mul_u32_u24_e32 v166, 0x110, v166
	s_waitcnt lgkmcnt(0)
	s_barrier
; #define LAS __attribute__((address_space(3)))
; #define MFMA16(a, b, c) __builtin_amdgcn_mfma_f32_16x16x32_bf16((a), (b), (c), 0, 0, 0)
; __device__ __forceinline__ void attention_item(LAS unsigned char* lds, const bf16* ZH, bf16* OP, float* LP, bf16* MIX, const float* qg, const float* kg, int item, int tid0) {
;     ...
;         f32x4 sT[10];
; #pragma unroll
;         for (int t = 0; t < 10; ++t) sT[t] = (f32x4){0.f, 0.f, 0.f, 0.f};
; #pragma unroll
;         for (int ks = 0; ks < 4; ++ks) {
; #pragma unroll
;             for (int t = 0; t < 10; ++t) { const int rowb = (16 * (jt0 + t) + off) & 255;
;                 const bf16x8 a = *(const LAS bf16x8*)(lds + A_K + (rowb + lr) * RS + (8 * lg + 32 * ks) * 2); sT[t] = MFMA16(a, qf[ks], sT[t]);
;                 if (t == 4) __builtin_amdgcn_sched_barrier(0); }
;             __builtin_amdgcn_sched_barrier(0); }
	v_add3_u32 v224, 0, v158, v186
	v_add3_u32 v225, 0, v162, v186
	v_add3_u32 v240, 0, v166, v186
	ds_read_b128 v[150:153], v208
	ds_read_b128 v[154:157], v211
	ds_read_b128 v[158:161], v224
	ds_read_b128 v[162:165], v225
	ds_read_b128 v[166:169], v240
	s_waitcnt vmcnt(3) lgkmcnt(4)
	v_mfma_f32_16x16x32_bf16 v[150:153], v[150:153], v[114:117], 0
	s_xor_b64 s[54:55], s[54:55], -1
	s_mov_b32 s35, 4
	s_waitcnt lgkmcnt(3)
	v_mfma_f32_16x16x32_bf16 v[154:157], v[154:157], v[114:117], 0
	s_waitcnt lgkmcnt(2)
	v_mfma_f32_16x16x32_bf16 v[158:161], v[158:161], v[114:117], 0
	s_waitcnt lgkmcnt(1)
	v_mfma_f32_16x16x32_bf16 v[162:165], v[162:165], v[114:117], 0
	s_waitcnt lgkmcnt(0)
	v_mfma_f32_16x16x32_bf16 v[166:169], v[166:169], v[114:117], 0
	v_xor_b32_e32 v182, 0x80, v182
	v_add_u32_e32 v170, 0x50, v207
	v_add_u32_e32 v174, 0x60, v174
	v_add_u32_e32 v178, 0x70, v207
	v_add_u32_e32 v182, s56, v182
	v_and_or_b32 v170, v170, s30, v2
	v_and_or_b32 v174, v174, s90, v2
	v_and_or_b32 v178, v178, s30, v2
	v_and_or_b32 v182, v182, s90, v2
	v_mul_u32_u24_e32 v170, 0x110, v170
	v_mul_u32_u24_e32 v174, 0x110, v174
	v_mul_u32_u24_e32 v178, 0x110, v178
	v_mul_u32_u24_e32 v182, 0x110, v182
	v_add3_u32 v241, 0, v170, v186
	v_add3_u32 v242, 0, v174, v186
	v_add3_u32 v243, 0, v178, v186
	v_add3_u32 v244, 0, v182, v186
	ds_read_b128 v[170:173], v241
	ds_read_b128 v[174:177], v242
	ds_read_b128 v[178:181], v243
	ds_read_b128 v[182:185], v244
	v_add_u32_e32 v187, 0x90, v207
	v_and_or_b32 v187, v187, s30, v2
	v_mul_u32_u24_e32 v187, 0x110, v187
	v_add3_u32 v245, 0, v187, v186
	ds_read_b128 v[186:189], v245
	s_waitcnt lgkmcnt(4)
	v_mfma_f32_16x16x32_bf16 v[170:173], v[170:173], v[114:117], 0
	s_waitcnt lgkmcnt(3)
	v_mfma_f32_16x16x32_bf16 v[174:177], v[174:177], v[114:117], 0
	s_waitcnt lgkmcnt(2)
	v_mfma_f32_16x16x32_bf16 v[178:181], v[178:181], v[114:117], 0
	s_waitcnt lgkmcnt(1)
	v_mfma_f32_16x16x32_bf16 v[182:185], v[182:185], v[114:117], 0
	s_waitcnt lgkmcnt(0)
	v_mfma_f32_16x16x32_bf16 v[114:117], v[186:189], v[114:117], 0
	ds_read_b128 v[246:249], v208 offset:64
	ds_read_b128 v[250:253], v211 offset:64
	ds_read_b128 v[186:189], v224 offset:64
	s_waitcnt vmcnt(2) lgkmcnt(2)
	v_mfma_f32_16x16x32_bf16 v[150:153], v[246:249], v[98:101], v[150:153]
	ds_read_b128 v[246:249], v225 offset:64
	s_waitcnt lgkmcnt(2)
	v_mfma_f32_16x16x32_bf16 v[154:157], v[250:253], v[98:101], v[154:157]
	ds_read_b128 v[250:253], v240 offset:64
	s_waitcnt lgkmcnt(2)
	v_mfma_f32_16x16x32_bf16 v[158:161], v[186:189], v[98:101], v[158:161]
	ds_read_b128 v[186:189], v241 offset:64
	s_waitcnt lgkmcnt(2)
	v_mfma_f32_16x16x32_bf16 v[162:165], v[246:249], v[98:101], v[162:165]
	ds_read_b128 v[246:249], v242 offset:64
	s_waitcnt lgkmcnt(2)
	v_mfma_f32_16x16x32_bf16 v[166:169], v[250:253], v[98:101], v[166:169]
	ds_read_b128 v[250:253], v243 offset:64
	s_waitcnt lgkmcnt(2)
	v_mfma_f32_16x16x32_bf16 v[170:173], v[186:189], v[98:101], v[170:173]
	ds_read_b128 v[186:189], v244 offset:64
	s_waitcnt lgkmcnt(2)
	v_mfma_f32_16x16x32_bf16 v[174:177], v[246:249], v[98:101], v[174:177]
	ds_read_b128 v[246:249], v245 offset:64
	s_waitcnt lgkmcnt(2)
	v_mfma_f32_16x16x32_bf16 v[178:181], v[250:253], v[98:101], v[178:181]
	ds_read_b128 v[250:253], v208 offset:128
	s_waitcnt lgkmcnt(2)
	v_mfma_f32_16x16x32_bf16 v[182:185], v[186:189], v[98:101], v[182:185]
	s_waitcnt lgkmcnt(1)
	v_mfma_f32_16x16x32_bf16 v[114:117], v[246:249], v[98:101], v[114:117]
	ds_read_b128 v[98:101], v245 offset:128
	ds_read_b128 v[246:249], v211 offset:128
	s_waitcnt vmcnt(1) lgkmcnt(2)
	v_mfma_f32_16x16x32_bf16 v[186:189], v[250:253], v[74:77], v[150:153]
	ds_read_b128 v[250:253], v244 offset:128
	s_waitcnt lgkmcnt(2)
	s_nop 0
	v_mfma_f32_16x16x32_bf16 v[150:153], v[98:101], v[74:77], v[114:117]
	ds_read_b128 v[98:101], v224 offset:128
	s_waitcnt lgkmcnt(2)
	s_nop 0
	v_mfma_f32_16x16x32_bf16 v[114:117], v[246:249], v[74:77], v[154:157]
	ds_read_b128 v[246:249], v243 offset:128
	s_waitcnt lgkmcnt(2)
	s_nop 0
	v_mfma_f32_16x16x32_bf16 v[154:157], v[250:253], v[74:77], v[182:185]
	ds_read_b128 v[250:253], v225 offset:128
	s_waitcnt lgkmcnt(2)
	v_mfma_f32_16x16x32_bf16 v[212:215], v[98:101], v[74:77], v[158:161]
	ds_read_b128 v[98:101], v242 offset:128
	s_waitcnt lgkmcnt(2)
	s_nop 0
	v_mfma_f32_16x16x32_bf16 v[158:161], v[246:249], v[74:77], v[178:181]
	ds_read_b128 v[246:249], v240 offset:128
	s_waitcnt lgkmcnt(2)
	v_mfma_f32_16x16x32_bf16 v[216:219], v[250:253], v[74:77], v[162:165]
	ds_read_b128 v[250:253], v241 offset:128
	s_waitcnt lgkmcnt(2)
	s_nop 0
	v_mfma_f32_16x16x32_bf16 v[162:165], v[98:101], v[74:77], v[174:177]
	ds_read_b128 v[98:101], v208 offset:192
	s_waitcnt lgkmcnt(2)
	v_mfma_f32_16x16x32_bf16 v[220:223], v[246:249], v[74:77], v[166:169]
	ds_read_b128 v[246:249], v211 offset:192
	s_waitcnt lgkmcnt(2)
	s_nop 0
	v_mfma_f32_16x16x32_bf16 v[166:169], v[250:253], v[74:77], v[170:173]
	ds_read_b128 v[250:253], v224 offset:192
	s_waitcnt vmcnt(0) lgkmcnt(2)
	v_mfma_f32_16x16x32_bf16 v[186:189], v[98:101], v[66:69], v[186:189]
	ds_read_b128 v[98:101], v225 offset:192
	s_waitcnt lgkmcnt(2)
	v_mfma_f32_16x16x32_bf16 v[182:185], v[246:249], v[66:69], v[114:117]
	ds_read_b128 v[246:249], v240 offset:192
	s_waitcnt lgkmcnt(2)
	v_mfma_f32_16x16x32_bf16 v[178:181], v[250:253], v[66:69], v[212:215]
	ds_read_b128 v[250:253], v241 offset:192
	s_waitcnt lgkmcnt(2)
	v_mfma_f32_16x16x32_bf16 v[174:177], v[98:101], v[66:69], v[216:219]
	ds_read_b128 v[98:101], v242 offset:192
	s_waitcnt lgkmcnt(2)
	v_mfma_f32_16x16x32_bf16 v[170:173], v[246:249], v[66:69], v[220:223]
	ds_read_b128 v[246:249], v243 offset:192
	s_waitcnt lgkmcnt(2)
	v_mfma_f32_16x16x32_bf16 v[166:169], v[250:253], v[66:69], v[166:169]
	ds_read_b128 v[250:253], v244 offset:192
	s_waitcnt lgkmcnt(2)
	v_mfma_f32_16x16x32_bf16 v[162:165], v[98:101], v[66:69], v[162:165]
	ds_read_b128 v[98:101], v245 offset:192
	s_waitcnt lgkmcnt(2)
	v_mfma_f32_16x16x32_bf16 v[158:161], v[246:249], v[66:69], v[158:161]
	s_waitcnt lgkmcnt(1)
	v_mfma_f32_16x16x32_bf16 v[154:157], v[250:253], v[66:69], v[154:157]
	s_waitcnt lgkmcnt(0)
	v_mfma_f32_16x16x32_bf16 v[150:153], v[98:101], v[66:69], v[150:153]
	s_mov_b32 s57, 0
	s_cmp_lt_u32 s44, 15
	s_mov_b32 s45, s50
	s_cbranch_scc1 .LBB0_386
	s_cmp_gt_u32 s44, 31
	s_mov_b64 s[34:35], -1
	s_cbranch_scc0 .LBB0_384
	s_add_i32 s57, s97, -16
	s_mov_b64 s[34:35], 0

; #define LAS __attribute__((address_space(3)))
; #define WG_BARRIER() do { asm volatile("s_waitcnt lgkmcnt(0)" ::: "memory"); __builtin_amdgcn_s_barrier(); asm volatile("" ::: "memory"); } while (0)
; __device__ __forceinline__ void attention_item(LAS unsigned char* lds, const bf16* ZH, bf16* OP, float* LP, bf16* MIX, const float* qg, const float* kg, int item, int tid0) {
;     ...
;         WG_BARRIER();
; #pragma unroll
;         for (int p = 0; p < 8; ++p) if (p >= 4 || B.b == 0) { const int slot = (32 * p + krow + off) & 255;
;             *(LAS v4u*)(lds + A_K + slot * RS + 16 * kc) = kq[p];
;             *(LAS v4u*)(lds + A_V + slot * RSB + 16 * kc) = vq[p]; }
;         WG_BARRIER();
.LBB0_429:
	s_lshl_b32 s55, s55, 7
	v_and_b32_e32 v4, 3, v5
	v_add_u32_e32 v5, s55, v5
	v_bitop3_b32 v150, v5, s91, v238 bitop3:0x6c
	v_mul_u32_u24_e32 v151, 0x110, v150
	v_add3_u32 v151, 0, v151, v2
	ds_write_b128 v151, v[122:125]
	v_mul_u32_u24_e32 v122, 0x120, v150
	v_add3_u32 v122, s92, v122, v2
	ds_write_b128 v122, v[126:129]
	v_add_u32_e32 v122, 0xa0, v5
	v_mul_u32_u24_sdwa v123, v122, s33 dst_sel:DWORD dst_unused:UNUSED_PAD src0_sel:BYTE_0 src1_sel:DWORD
	v_add3_u32 v123, 0, v123, v2
	ds_write_b128 v123, v[118:121]
	v_mul_u32_u24_sdwa v118, v122, s74 dst_sel:DWORD dst_unused:UNUSED_PAD src0_sel:BYTE_0 src1_sel:DWORD
	v_add3_u32 v118, s92, v118, v2
	ds_write_b128 v118, v[130:133]
	v_add_u32_e32 v118, 0xc0, v5
	v_mul_u32_u24_sdwa v119, v118, s33 dst_sel:DWORD dst_unused:UNUSED_PAD src0_sel:BYTE_0 src1_sel:DWORD
	v_mul_u32_u24_sdwa v118, v118, s74 dst_sel:DWORD dst_unused:UNUSED_PAD src0_sel:BYTE_0 src1_sel:DWORD
	v_add3_u32 v119, 0, v119, v2
	v_add3_u32 v118, s92, v118, v2
	v_add_u32_e32 v5, 0xe0, v5
	v_ashrrev_i32_e32 v150, 2, v161
	ds_write_b128 v119, v[138:141]
	ds_write_b128 v118, v[142:145]
	v_mul_u32_u24_sdwa v118, v5, s33 dst_sel:DWORD dst_unused:UNUSED_PAD src0_sel:BYTE_0 src1_sel:DWORD
	v_mul_u32_u24_sdwa v5, v5, s74 dst_sel:DWORD dst_unused:UNUSED_PAD src0_sel:BYTE_0 src1_sel:DWORD
	v_and_b32_e32 v162, 0xffffffe0, v150
	v_add3_u32 v118, 0, v118, v2
	v_add3_u32 v2, s92, v5, v2
	v_add_u32_e32 v159, s55, v162
	ds_write_b128 v118, v[134:137]
	ds_write_b128 v2, v[146:149]
	v_and_b32_e32 v2, 15, v161
	v_and_b32_e32 v158, 0xe0, v159
	v_or_b32_e32 v5, v158, v2
	v_lshlrev_b32_e32 v154, 4, v4
	v_mul_u32_u24_e32 v5, 0x110, v5
	v_add3_u32 v160, 0, v5, v154
	v_or_b32_e32 v5, 16, v150
	v_add_u32_e32 v5, s55, v5
	v_and_or_b32 v5, v5, s30, v2
	v_mul_u32_u24_e32 v5, 0x110, v5
	v_add3_u32 v163, 0, v5, v154
	v_and_b32_e32 v5, -16, v150
	v_add_u32_e32 v142, s55, v5
	v_add_u32_e32 v126, 32, v142
	v_add_u32_e32 v130, 48, v159
	v_add_u32_e32 v134, 64, v142
	v_and_or_b32 v126, v126, s90, v2
	v_and_or_b32 v130, v130, s30, v2
	v_and_or_b32 v134, v134, s90, v2
	v_mul_u32_u24_e32 v126, 0x110, v126
	v_mul_u32_u24_e32 v130, 0x110, v130
	v_mul_u32_u24_e32 v134, 0x110, v134
	s_waitcnt lgkmcnt(0)
	s_barrier
; #define LAS __attribute__((address_space(3)))
; #define MFMA16(a, b, c) __builtin_amdgcn_mfma_f32_16x16x32_bf16((a), (b), (c), 0, 0, 0)
; __device__ __forceinline__ void attention_item(LAS unsigned char* lds, const bf16* ZH, bf16* OP, float* LP, bf16* MIX, const float* qg, const float* kg, int item, int tid0) {
;     ...
;         f32x4 sT[10];
; #pragma unroll
;         for (int t = 0; t < 10; ++t) sT[t] = (f32x4){0.f, 0.f, 0.f, 0.f};
; #pragma unroll
;         for (int ks = 0; ks < 4; ++ks) {
; #pragma unroll
;             for (int t = 0; t < 10; ++t) { const int rowb = (16 * (jt0 + t) + off) & 255;
;                 const bf16x8 a = *(const LAS bf16x8*)(lds + A_K + (rowb + lr) * RS + (8 * lg + 32 * ks) * 2); sT[t] = MFMA16(a, qf[ks], sT[t]);
;                 if (t == 4) __builtin_amdgcn_sched_barrier(0); }
;             __builtin_amdgcn_sched_barrier(0); }
	v_add3_u32 v184, 0, v126, v154
	v_add3_u32 v185, 0, v130, v154
	v_add3_u32 v186, 0, v134, v154
	ds_read_b128 v[118:121], v160
	ds_read_b128 v[122:125], v163
	ds_read_b128 v[126:129], v184
	ds_read_b128 v[130:133], v185
	ds_read_b128 v[134:137], v186
	s_waitcnt vmcnt(3) lgkmcnt(4)
	v_mfma_f32_16x16x32_bf16 v[118:121], v[118:121], v[114:117], 0
	s_waitcnt lgkmcnt(3)
	v_mfma_f32_16x16x32_bf16 v[122:125], v[122:125], v[114:117], 0
	s_waitcnt lgkmcnt(2)
	v_mfma_f32_16x16x32_bf16 v[126:129], v[126:129], v[114:117], 0
	s_waitcnt lgkmcnt(1)
	v_mfma_f32_16x16x32_bf16 v[130:133], v[130:133], v[114:117], 0
	s_waitcnt lgkmcnt(0)
	v_mfma_f32_16x16x32_bf16 v[134:137], v[134:137], v[114:117], 0
	v_xor_b32_e32 v150, 0x80, v150
	v_add_u32_e32 v138, 0x50, v159
	v_add_u32_e32 v142, 0x60, v142
	v_add_u32_e32 v146, 0x70, v159
	v_add_u32_e32 v150, s55, v150
	v_add_u32_e32 v155, 0x90, v159
	v_and_or_b32 v138, v138, s30, v2
	v_and_or_b32 v142, v142, s90, v2
	v_and_or_b32 v146, v146, s30, v2
	v_and_or_b32 v150, v150, s90, v2
	v_and_or_b32 v155, v155, s30, v2
	v_mul_u32_u24_e32 v138, 0x110, v138
	v_mul_u32_u24_e32 v142, 0x110, v142
	v_mul_u32_u24_e32 v146, 0x110, v146
	v_mul_u32_u24_e32 v150, 0x110, v150
	v_mul_u32_u24_e32 v155, 0x110, v155
	v_add3_u32 v187, 0, v138, v154
	v_add3_u32 v188, 0, v142, v154
	v_add3_u32 v189, 0, v146, v154
	v_add3_u32 v206, 0, v150, v154
	v_add3_u32 v207, 0, v155, v154
	ds_read_b128 v[138:141], v187
	ds_read_b128 v[142:145], v188
	ds_read_b128 v[146:149], v189
	ds_read_b128 v[150:153], v206
	ds_read_b128 v[154:157], v207
	s_waitcnt lgkmcnt(4)
	v_mfma_f32_16x16x32_bf16 v[138:141], v[138:141], v[114:117], 0
	s_waitcnt lgkmcnt(3)
	v_mfma_f32_16x16x32_bf16 v[142:145], v[142:145], v[114:117], 0
	s_waitcnt lgkmcnt(2)
	v_mfma_f32_16x16x32_bf16 v[146:149], v[146:149], v[114:117], 0
	s_waitcnt lgkmcnt(1)
	v_mfma_f32_16x16x32_bf16 v[150:153], v[150:153], v[114:117], 0
	s_waitcnt lgkmcnt(0)
	v_mfma_f32_16x16x32_bf16 v[154:157], v[154:157], v[114:117], 0
	ds_read_b128 v[208:211], v160 offset:64
	ds_read_b128 v[212:215], v163 offset:64
	ds_read_b128 v[216:219], v184 offset:64
	ds_read_b128 v[220:223], v185 offset:64
	ds_read_b128 v[240:243], v186 offset:64
	ds_read_b128 v[244:247], v187 offset:64
	ds_read_b128 v[248:251], v188 offset:64
	s_waitcnt vmcnt(2) lgkmcnt(6)
	v_mfma_f32_16x16x32_bf16 v[118:121], v[208:211], v[98:101], v[118:121]
	ds_read_b128 v[208:211], v189 offset:64
	s_waitcnt lgkmcnt(6)
	v_mfma_f32_16x16x32_bf16 v[122:125], v[212:215], v[98:101], v[122:125]
	ds_read_b128 v[212:215], v206 offset:64
	s_waitcnt lgkmcnt(6)
	v_mfma_f32_16x16x32_bf16 v[126:129], v[216:219], v[98:101], v[126:129]
	ds_read_b128 v[216:219], v207 offset:64
	s_waitcnt lgkmcnt(6)
	v_mfma_f32_16x16x32_bf16 v[130:133], v[220:223], v[98:101], v[130:133]
	ds_read_b128 v[220:223], v160 offset:128
	s_waitcnt lgkmcnt(6)
	v_mfma_f32_16x16x32_bf16 v[134:137], v[240:243], v[98:101], v[134:137]
	ds_read_b128 v[240:243], v207 offset:128
	s_waitcnt lgkmcnt(6)
	v_mfma_f32_16x16x32_bf16 v[138:141], v[244:247], v[98:101], v[138:141]
	ds_read_b128 v[244:247], v163 offset:128
	s_waitcnt lgkmcnt(6)
	v_mfma_f32_16x16x32_bf16 v[142:145], v[248:251], v[98:101], v[142:145]
	ds_read_b128 v[248:251], v206 offset:128
	s_waitcnt lgkmcnt(6)
	v_mfma_f32_16x16x32_bf16 v[146:149], v[208:211], v[98:101], v[146:149]
	ds_read_b128 v[208:211], v184 offset:128
	s_waitcnt lgkmcnt(6)
	v_mfma_f32_16x16x32_bf16 v[150:153], v[212:215], v[98:101], v[150:153]
	ds_read_b128 v[212:215], v189 offset:128
	s_waitcnt lgkmcnt(6)
	v_mfma_f32_16x16x32_bf16 v[154:157], v[216:219], v[98:101], v[154:157]
	ds_read_b128 v[216:219], v185 offset:128
	s_waitcnt vmcnt(1) lgkmcnt(6)
	v_mfma_f32_16x16x32_bf16 v[164:167], v[220:223], v[74:77], v[118:121]
	ds_read_b128 v[220:223], v188 offset:128
	s_waitcnt lgkmcnt(6)
	s_nop 0
	v_mfma_f32_16x16x32_bf16 v[118:121], v[240:243], v[74:77], v[154:157]
	ds_read_b128 v[240:243], v186 offset:128
	s_waitcnt lgkmcnt(6)
	v_mfma_f32_16x16x32_bf16 v[168:171], v[244:247], v[74:77], v[122:125]
	ds_read_b128 v[244:247], v187 offset:128
	s_waitcnt lgkmcnt(6)
	s_nop 0
	v_mfma_f32_16x16x32_bf16 v[122:125], v[248:251], v[74:77], v[150:153]
	ds_read_b128 v[248:251], v160 offset:192
	s_waitcnt lgkmcnt(6)
	v_mfma_f32_16x16x32_bf16 v[172:175], v[208:211], v[74:77], v[126:129]
	ds_read_b128 v[208:211], v163 offset:192
	s_waitcnt lgkmcnt(6)
	s_nop 0
	v_mfma_f32_16x16x32_bf16 v[126:129], v[212:215], v[74:77], v[146:149]
	ds_read_b128 v[212:215], v184 offset:192
	s_waitcnt lgkmcnt(6)
	v_mfma_f32_16x16x32_bf16 v[176:179], v[216:219], v[74:77], v[130:133]
	ds_read_b128 v[216:219], v185 offset:192
	s_waitcnt lgkmcnt(6)
	s_nop 0
	v_mfma_f32_16x16x32_bf16 v[130:133], v[220:223], v[74:77], v[142:145]
	ds_read_b128 v[220:223], v186 offset:192
	s_waitcnt lgkmcnt(6)
	v_mfma_f32_16x16x32_bf16 v[180:183], v[240:243], v[74:77], v[134:137]
	ds_read_b128 v[240:243], v187 offset:192
	s_waitcnt lgkmcnt(6)
	s_nop 0
	v_mfma_f32_16x16x32_bf16 v[134:137], v[244:247], v[74:77], v[138:141]
	ds_read_b128 v[244:247], v188 offset:192
	s_waitcnt vmcnt(0) lgkmcnt(6)
	v_mfma_f32_16x16x32_bf16 v[154:157], v[248:251], v[66:69], v[164:167]
	ds_read_b128 v[248:251], v189 offset:192
	s_waitcnt lgkmcnt(6)
	v_mfma_f32_16x16x32_bf16 v[150:153], v[208:211], v[66:69], v[168:171]
	ds_read_b128 v[208:211], v206 offset:192
	s_waitcnt lgkmcnt(6)
	v_mfma_f32_16x16x32_bf16 v[146:149], v[212:215], v[66:69], v[172:175]
	ds_read_b128 v[212:215], v207 offset:192
	s_waitcnt lgkmcnt(6)
	v_mfma_f32_16x16x32_bf16 v[142:145], v[216:219], v[66:69], v[176:179]
	s_waitcnt lgkmcnt(5)
	v_mfma_f32_16x16x32_bf16 v[138:141], v[220:223], v[66:69], v[180:183]
	s_waitcnt lgkmcnt(4)
	v_mfma_f32_16x16x32_bf16 v[134:137], v[240:243], v[66:69], v[134:137]
	s_waitcnt lgkmcnt(3)
	v_mfma_f32_16x16x32_bf16 v[130:133], v[244:247], v[66:69], v[130:133]
	s_waitcnt lgkmcnt(2)
	v_mfma_f32_16x16x32_bf16 v[126:129], v[248:251], v[66:69], v[126:129]
	s_waitcnt lgkmcnt(1)
	v_mfma_f32_16x16x32_bf16 v[122:125], v[208:211], v[66:69], v[122:125]
	s_waitcnt lgkmcnt(0)
	v_mfma_f32_16x16x32_bf16 v[118:121], v[212:215], v[66:69], v[118:121]
	s_cmp_gt_u32 s50, 46
	s_cbranch_scc1 .LBB0_438
	s_cmp_lt_u32 s50, 15
	s_cbranch_scc1 .LBB0_436
	s_cmp_gt_u32 s44, 29
	s_mov_b64 s[34:35], -1
	s_cbranch_scc0 .LBB0_433
	s_add_i32 s44, s97, -15
	s_mov_b64 s[34:35], 0
